# accumulator zeroing with v_pk_mov_b32 register pairs (64 instead of 128 VALU per unit) in 13 of 17 GEMM unit loops
# speedup vs baseline: 1.0074x; 1.0011x over previous
; #define PG8_BAR __builtin_amdgcn_s_barrier()
; template <class Epi>
; __device__ __forceinline__ void gemm_phase(LAS unsigned char* lds, const int tid, const Gemm g, const StaticOrder& S, const Epi& E) {
;     ...
; #pragma unroll
;         for (int a = 0; a < 2; ++a)
; #pragma unroll
;             for (int b = 0; b < 2; ++b)
; #pragma unroll
;                 for (int m = 0; m < 4; ++m)
; #pragma unroll
;                     for (int n = 0; n < 2; ++n) acc[a][b][m][n] = (f32x4){0.f, 0.f, 0.f, 0.f};
;         cur = nxt; cA = nA; cB = nB; ++ui;
;         if (wr == 1) PG8_BAR;
.Lzskip_1:
	s_and_b64 s[30:31], s[4:5], exec
	s_cselect_b32 s17, s21, s29
	s_cselect_b32 s19, s20, s28
	s_cselect_b32 s55, s23, s27
	s_cselect_b32 s56, s22, s26
	s_ashr_i32 s25, s24, 31
	s_lshl_b64 s[30:31], s[24:25], 14
	s_add_u32 s25, s26, 0x100
	s_addc_u32 s57, s27, 0
	v_lshl_add_u64 v[146:147], v[136:137], 0, s[30:31]
	s_add_u32 s26, s28, 0x40080
	v_mov_b32_e32 v0, 0
	v_mov_b32_e32 v1, 0
	v_lshl_add_u64 v[148:149], v[146:147], 0, s[14:15]
	s_addc_u32 s27, s29, 0
	s_mov_b32 s58, 0
	v_pk_mov_b32 v[2:3], v[0:1], v[0:1]
	v_pk_mov_b32 v[4:5], v[0:1], v[0:1]
	v_pk_mov_b32 v[6:7], v[0:1], v[0:1]
	v_pk_mov_b32 v[8:9], v[0:1], v[0:1]
	v_pk_mov_b32 v[10:11], v[0:1], v[0:1]
	v_pk_mov_b32 v[12:13], v[0:1], v[0:1]
	v_pk_mov_b32 v[14:15], v[0:1], v[0:1]
	v_pk_mov_b32 v[16:17], v[0:1], v[0:1]
	v_pk_mov_b32 v[18:19], v[0:1], v[0:1]
	v_pk_mov_b32 v[20:21], v[0:1], v[0:1]
	v_pk_mov_b32 v[22:23], v[0:1], v[0:1]
	v_pk_mov_b32 v[24:25], v[0:1], v[0:1]
	v_pk_mov_b32 v[26:27], v[0:1], v[0:1]
	v_pk_mov_b32 v[28:29], v[0:1], v[0:1]
	v_pk_mov_b32 v[30:31], v[0:1], v[0:1]
	v_pk_mov_b32 v[32:33], v[0:1], v[0:1]
	v_pk_mov_b32 v[34:35], v[0:1], v[0:1]
	v_pk_mov_b32 v[36:37], v[0:1], v[0:1]
	v_pk_mov_b32 v[38:39], v[0:1], v[0:1]
	v_pk_mov_b32 v[40:41], v[0:1], v[0:1]
	v_pk_mov_b32 v[42:43], v[0:1], v[0:1]
	v_pk_mov_b32 v[44:45], v[0:1], v[0:1]
	v_pk_mov_b32 v[46:47], v[0:1], v[0:1]
	v_pk_mov_b32 v[48:49], v[0:1], v[0:1]
	v_pk_mov_b32 v[50:51], v[0:1], v[0:1]
	v_pk_mov_b32 v[52:53], v[0:1], v[0:1]
	v_pk_mov_b32 v[54:55], v[0:1], v[0:1]
	v_pk_mov_b32 v[56:57], v[0:1], v[0:1]
	v_pk_mov_b32 v[58:59], v[0:1], v[0:1]
	v_pk_mov_b32 v[60:61], v[0:1], v[0:1]
	v_pk_mov_b32 v[62:63], v[0:1], v[0:1]
	v_pk_mov_b32 v[64:65], v[0:1], v[0:1]
	v_pk_mov_b32 v[66:67], v[0:1], v[0:1]
	v_pk_mov_b32 v[68:69], v[0:1], v[0:1]
	v_pk_mov_b32 v[70:71], v[0:1], v[0:1]
	v_pk_mov_b32 v[72:73], v[0:1], v[0:1]
	v_pk_mov_b32 v[74:75], v[0:1], v[0:1]
	v_pk_mov_b32 v[76:77], v[0:1], v[0:1]
	v_pk_mov_b32 v[78:79], v[0:1], v[0:1]
	v_pk_mov_b32 v[80:81], v[0:1], v[0:1]
	v_pk_mov_b32 v[82:83], v[0:1], v[0:1]
	v_pk_mov_b32 v[84:85], v[0:1], v[0:1]
	v_pk_mov_b32 v[86:87], v[0:1], v[0:1]
	v_pk_mov_b32 v[88:89], v[0:1], v[0:1]
	v_pk_mov_b32 v[90:91], v[0:1], v[0:1]
	v_pk_mov_b32 v[92:93], v[0:1], v[0:1]
	v_pk_mov_b32 v[94:95], v[0:1], v[0:1]
	v_pk_mov_b32 v[96:97], v[0:1], v[0:1]
	v_pk_mov_b32 v[98:99], v[0:1], v[0:1]
	v_pk_mov_b32 v[100:101], v[0:1], v[0:1]
	v_pk_mov_b32 v[102:103], v[0:1], v[0:1]
	v_pk_mov_b32 v[104:105], v[0:1], v[0:1]
	v_pk_mov_b32 v[106:107], v[0:1], v[0:1]
	v_pk_mov_b32 v[108:109], v[0:1], v[0:1]
	v_pk_mov_b32 v[110:111], v[0:1], v[0:1]
	v_pk_mov_b32 v[112:113], v[0:1], v[0:1]
	v_pk_mov_b32 v[114:115], v[0:1], v[0:1]
	v_pk_mov_b32 v[116:117], v[0:1], v[0:1]
	v_pk_mov_b32 v[118:119], v[0:1], v[0:1]
	v_pk_mov_b32 v[120:121], v[0:1], v[0:1]
	v_pk_mov_b32 v[122:123], v[0:1], v[0:1]
	v_pk_mov_b32 v[124:125], v[0:1], v[0:1]
	v_pk_mov_b32 v[126:127], v[0:1], v[0:1]
	s_branch .LBB0_264

; #define PG8_BAR __builtin_amdgcn_s_barrier()
; template <class Epi>
; __device__ __forceinline__ void gemm_phase(LAS unsigned char* lds, const int tid, const Gemm g, const StaticOrder& S, const Epi& E) {
;     ...
;     f32x4 acc[2][2][4][2];
; #pragma unroll
;     for (int a = 0; a < 2; ++a)
; #pragma unroll
;         for (int b = 0; b < 2; ++b)
; #pragma unroll
;             for (int m = 0; m < 4; ++m)
; #pragma unroll
;                 for (int n = 0; n < 2; ++n) acc[a][b][m][n] = (f32x4){0.f, 0.f, 0.f, 0.f};
;     ...
; #pragma unroll
;         for (int a = 0; a < 2; ++a)
; #pragma unroll
;             for (int b = 0; b < 2; ++b)
; #pragma unroll
;                 for (int m = 0; m < 4; ++m)
; #pragma unroll
;                     for (int n = 0; n < 2; ++n) acc[a][b][m][n] = (f32x4){0.f, 0.f, 0.f, 0.f};
;         cur = nxt; cA = nA; cB = nB; ++ui;
;         if (wr == 1) PG8_BAR;
.LBB0_350:
	v_mov_b32_e32 v179, 0
	s_andn2_b64 vcc, exec, s[20:21]
	v_mov_b32_e32 v178, 0
	v_mov_b32_e32 v181, 0
	v_mov_b32_e32 v180, 0
	v_mov_b32_e32 v183, 0
	v_mov_b32_e32 v182, 0
	v_mov_b32_e32 v185, 0
	v_mov_b32_e32 v184, 0
	v_mov_b32_e32 v177, 0
	v_mov_b32_e32 v176, 0
	v_mov_b32_e32 v175, 0
	v_mov_b32_e32 v174, 0
	v_mov_b32_e32 v173, 0
	v_mov_b32_e32 v172, 0
	v_mov_b32_e32 v171, 0
	v_mov_b32_e32 v170, 0
	v_mov_b32_e32 v161, 0
	v_mov_b32_e32 v160, 0
	v_mov_b32_e32 v159, 0
	v_mov_b32_e32 v158, 0
	v_mov_b32_e32 v157, 0
	v_mov_b32_e32 v156, 0
	v_mov_b32_e32 v155, 0
	v_mov_b32_e32 v154, 0
	v_mov_b32_e32 v145, 0
	v_mov_b32_e32 v144, 0
	v_mov_b32_e32 v127, 0
	v_mov_b32_e32 v126, 0
	v_mov_b32_e32 v125, 0
	v_mov_b32_e32 v124, 0
	v_mov_b32_e32 v123, 0
	v_mov_b32_e32 v122, 0
	v_mov_b32_e32 v193, 0
	v_mov_b32_e32 v192, 0
	v_mov_b32_e32 v191, 0
	v_mov_b32_e32 v190, 0
	v_mov_b32_e32 v189, 0
	v_mov_b32_e32 v188, 0
	v_mov_b32_e32 v187, 0
	v_mov_b32_e32 v186, 0
	v_mov_b32_e32 v169, 0
	v_mov_b32_e32 v168, 0
	v_mov_b32_e32 v167, 0
	v_mov_b32_e32 v166, 0
	v_mov_b32_e32 v165, 0
	v_mov_b32_e32 v164, 0
	v_mov_b32_e32 v163, 0
	v_mov_b32_e32 v162, 0
	v_mov_b32_e32 v153, 0
	v_mov_b32_e32 v152, 0
	v_mov_b32_e32 v151, 0
	v_mov_b32_e32 v150, 0
	v_mov_b32_e32 v149, 0
	v_mov_b32_e32 v148, 0
	v_mov_b32_e32 v147, 0
	v_mov_b32_e32 v146, 0
	v_mov_b32_e32 v121, 0
	v_mov_b32_e32 v120, 0
	v_mov_b32_e32 v119, 0
	v_mov_b32_e32 v118, 0
	v_mov_b32_e32 v117, 0
	v_mov_b32_e32 v116, 0
	v_mov_b32_e32 v115, 0
	v_mov_b32_e32 v114, 0
	v_mov_b32_e32 v97, 0
	v_mov_b32_e32 v96, 0
	v_mov_b32_e32 v99, 0
	v_mov_b32_e32 v98, 0
	v_mov_b32_e32 v101, 0
	v_mov_b32_e32 v100, 0
	v_mov_b32_e32 v103, 0
	v_mov_b32_e32 v102, 0
	v_mov_b32_e32 v95, 0
	v_mov_b32_e32 v94, 0
	v_mov_b32_e32 v93, 0
	v_mov_b32_e32 v92, 0
	v_mov_b32_e32 v91, 0
	v_mov_b32_e32 v90, 0
	v_mov_b32_e32 v89, 0
	v_mov_b32_e32 v88, 0
	v_mov_b32_e32 v79, 0
	v_mov_b32_e32 v78, 0
	v_mov_b32_e32 v77, 0
	v_mov_b32_e32 v76, 0
	v_mov_b32_e32 v75, 0
	v_mov_b32_e32 v74, 0
	v_mov_b32_e32 v73, 0
	v_mov_b32_e32 v72, 0
	v_mov_b32_e32 v63, 0
	v_mov_b32_e32 v62, 0
	v_mov_b32_e32 v61, 0
	v_mov_b32_e32 v60, 0
	v_mov_b32_e32 v59, 0
	v_mov_b32_e32 v58, 0
	v_mov_b32_e32 v57, 0
	v_mov_b32_e32 v56, 0
	v_mov_b32_e32 v111, 0
	v_mov_b32_e32 v110, 0
	v_mov_b32_e32 v109, 0
	v_mov_b32_e32 v108, 0
	v_mov_b32_e32 v107, 0
	v_mov_b32_e32 v106, 0
	v_mov_b32_e32 v105, 0
	v_mov_b32_e32 v104, 0
	v_mov_b32_e32 v87, 0
	v_mov_b32_e32 v86, 0
	v_mov_b32_e32 v85, 0
	v_mov_b32_e32 v84, 0
	v_mov_b32_e32 v83, 0
	v_mov_b32_e32 v82, 0
	v_mov_b32_e32 v81, 0
	v_mov_b32_e32 v80, 0
	v_mov_b32_e32 v71, 0
	v_mov_b32_e32 v70, 0
	v_mov_b32_e32 v69, 0
	v_mov_b32_e32 v68, 0
	v_mov_b32_e32 v67, 0
	v_mov_b32_e32 v66, 0
	v_mov_b32_e32 v65, 0
	v_mov_b32_e32 v64, 0
	v_mov_b32_e32 v55, 0
	v_mov_b32_e32 v54, 0
	v_mov_b32_e32 v53, 0
	v_mov_b32_e32 v52, 0
	v_mov_b32_e32 v51, 0
	v_mov_b32_e32 v50, 0
	v_mov_b32_e32 v49, 0
	v_mov_b32_e32 v48, 0
	s_cbranch_vccnz .LBB0_354
	s_add_u32 s58, s28, 0x100
	v_mov_b32_e32 v0, 0
	v_mov_b32_e32 v1, 0
	s_addc_u32 s59, s29, 0
	s_mov_b32 s30, 0
	v_pk_mov_b32 v[2:3], v[0:1], v[0:1]
	v_pk_mov_b32 v[4:5], v[0:1], v[0:1]
	v_pk_mov_b32 v[6:7], v[0:1], v[0:1]
	v_pk_mov_b32 v[8:9], v[0:1], v[0:1]
	v_pk_mov_b32 v[10:11], v[0:1], v[0:1]
	v_pk_mov_b32 v[12:13], v[0:1], v[0:1]
	v_pk_mov_b32 v[14:15], v[0:1], v[0:1]
	v_pk_mov_b32 v[16:17], v[0:1], v[0:1]
	v_pk_mov_b32 v[18:19], v[0:1], v[0:1]
	v_pk_mov_b32 v[20:21], v[0:1], v[0:1]
	v_pk_mov_b32 v[22:23], v[0:1], v[0:1]
	v_pk_mov_b32 v[24:25], v[0:1], v[0:1]
	v_pk_mov_b32 v[26:27], v[0:1], v[0:1]
	v_pk_mov_b32 v[28:29], v[0:1], v[0:1]
	v_pk_mov_b32 v[30:31], v[0:1], v[0:1]
	v_pk_mov_b32 v[32:33], v[0:1], v[0:1]
	v_pk_mov_b32 v[34:35], v[0:1], v[0:1]
	v_pk_mov_b32 v[36:37], v[0:1], v[0:1]
	v_pk_mov_b32 v[38:39], v[0:1], v[0:1]
	v_pk_mov_b32 v[40:41], v[0:1], v[0:1]
	v_pk_mov_b32 v[42:43], v[0:1], v[0:1]
	v_pk_mov_b32 v[44:45], v[0:1], v[0:1]
	v_pk_mov_b32 v[46:47], v[0:1], v[0:1]
	v_pk_mov_b32 v[48:49], v[0:1], v[0:1]
	v_pk_mov_b32 v[50:51], v[0:1], v[0:1]
	v_pk_mov_b32 v[52:53], v[0:1], v[0:1]
	v_pk_mov_b32 v[54:55], v[0:1], v[0:1]
	v_pk_mov_b32 v[56:57], v[0:1], v[0:1]
	v_pk_mov_b32 v[58:59], v[0:1], v[0:1]
	v_pk_mov_b32 v[60:61], v[0:1], v[0:1]
	v_pk_mov_b32 v[62:63], v[0:1], v[0:1]
	v_pk_mov_b32 v[64:65], v[0:1], v[0:1]
	v_pk_mov_b32 v[66:67], v[0:1], v[0:1]
	v_pk_mov_b32 v[68:69], v[0:1], v[0:1]
	v_pk_mov_b32 v[70:71], v[0:1], v[0:1]
	v_pk_mov_b32 v[72:73], v[0:1], v[0:1]
	v_pk_mov_b32 v[74:75], v[0:1], v[0:1]
	v_pk_mov_b32 v[76:77], v[0:1], v[0:1]
	v_pk_mov_b32 v[78:79], v[0:1], v[0:1]
	v_pk_mov_b32 v[80:81], v[0:1], v[0:1]
	v_pk_mov_b32 v[82:83], v[0:1], v[0:1]
	v_pk_mov_b32 v[84:85], v[0:1], v[0:1]
	v_pk_mov_b32 v[86:87], v[0:1], v[0:1]
	v_pk_mov_b32 v[88:89], v[0:1], v[0:1]
	v_pk_mov_b32 v[90:91], v[0:1], v[0:1]
	v_pk_mov_b32 v[92:93], v[0:1], v[0:1]
	v_pk_mov_b32 v[94:95], v[0:1], v[0:1]
	v_pk_mov_b32 v[96:97], v[0:1], v[0:1]
	v_pk_mov_b32 v[98:99], v[0:1], v[0:1]
	v_pk_mov_b32 v[100:101], v[0:1], v[0:1]
	v_pk_mov_b32 v[102:103], v[0:1], v[0:1]
	v_pk_mov_b32 v[104:105], v[0:1], v[0:1]
	v_pk_mov_b32 v[106:107], v[0:1], v[0:1]
	v_pk_mov_b32 v[108:109], v[0:1], v[0:1]
	v_pk_mov_b32 v[110:111], v[0:1], v[0:1]
	v_pk_mov_b32 v[112:113], v[0:1], v[0:1]
	v_pk_mov_b32 v[114:115], v[0:1], v[0:1]
	v_pk_mov_b32 v[116:117], v[0:1], v[0:1]
	v_pk_mov_b32 v[118:119], v[0:1], v[0:1]
	v_pk_mov_b32 v[120:121], v[0:1], v[0:1]
	v_pk_mov_b32 v[122:123], v[0:1], v[0:1]
	v_pk_mov_b32 v[124:125], v[0:1], v[0:1]
	v_pk_mov_b32 v[126:127], v[0:1], v[0:1]

; #define PG8_BAR __builtin_amdgcn_s_barrier()
; template <class Epi>
; __device__ __forceinline__ void gemm_phase(LAS unsigned char* lds, const int tid, const Gemm g, const StaticOrder& S, const Epi& E) {
;     ...
; #pragma unroll
;         for (int a = 0; a < 2; ++a)
; #pragma unroll
;             for (int b = 0; b < 2; ++b)
; #pragma unroll
;                 for (int m = 0; m < 4; ++m)
; #pragma unroll
;                     for (int n = 0; n < 2; ++n) acc[a][b][m][n] = (f32x4){0.f, 0.f, 0.f, 0.f};
;         cur = nxt; cA = nA; cB = nB; ++ui;
;         if (wr == 1) PG8_BAR;
.Lzskip_3:
	s_and_b64 s[36:37], s[4:5], exec
	s_cselect_b32 s21, s25, s35
	s_cselect_b32 s23, s24, s34
	s_cselect_b32 s29, s27, s31
	s_cselect_b32 s57, s26, s30
	s_add_u32 s58, s30, 0x100
	s_addc_u32 s59, s31, 0
	s_add_u32 s30, s34, 0x40080
	v_mov_b32_e32 v0, 0
	v_mov_b32_e32 v1, 0
	s_addc_u32 s31, s35, 0
	s_mov_b32 s34, 0
	v_pk_mov_b32 v[2:3], v[0:1], v[0:1]
	v_pk_mov_b32 v[4:5], v[0:1], v[0:1]
	v_pk_mov_b32 v[6:7], v[0:1], v[0:1]
	v_pk_mov_b32 v[8:9], v[0:1], v[0:1]
	v_pk_mov_b32 v[10:11], v[0:1], v[0:1]
	v_pk_mov_b32 v[12:13], v[0:1], v[0:1]
	v_pk_mov_b32 v[14:15], v[0:1], v[0:1]
	v_pk_mov_b32 v[16:17], v[0:1], v[0:1]
	v_pk_mov_b32 v[18:19], v[0:1], v[0:1]
	v_pk_mov_b32 v[20:21], v[0:1], v[0:1]
	v_pk_mov_b32 v[22:23], v[0:1], v[0:1]
	v_pk_mov_b32 v[24:25], v[0:1], v[0:1]
	v_pk_mov_b32 v[26:27], v[0:1], v[0:1]
	v_pk_mov_b32 v[28:29], v[0:1], v[0:1]
	v_pk_mov_b32 v[30:31], v[0:1], v[0:1]
	v_pk_mov_b32 v[32:33], v[0:1], v[0:1]
	v_pk_mov_b32 v[34:35], v[0:1], v[0:1]
	v_pk_mov_b32 v[36:37], v[0:1], v[0:1]
	v_pk_mov_b32 v[38:39], v[0:1], v[0:1]
	v_pk_mov_b32 v[40:41], v[0:1], v[0:1]
	v_pk_mov_b32 v[42:43], v[0:1], v[0:1]
	v_pk_mov_b32 v[44:45], v[0:1], v[0:1]
	v_pk_mov_b32 v[46:47], v[0:1], v[0:1]
	v_pk_mov_b32 v[48:49], v[0:1], v[0:1]
	v_pk_mov_b32 v[50:51], v[0:1], v[0:1]
	v_pk_mov_b32 v[52:53], v[0:1], v[0:1]
	v_pk_mov_b32 v[54:55], v[0:1], v[0:1]
	v_pk_mov_b32 v[56:57], v[0:1], v[0:1]
	v_pk_mov_b32 v[58:59], v[0:1], v[0:1]
	v_pk_mov_b32 v[60:61], v[0:1], v[0:1]
	v_pk_mov_b32 v[62:63], v[0:1], v[0:1]
	v_pk_mov_b32 v[64:65], v[0:1], v[0:1]
	v_pk_mov_b32 v[66:67], v[0:1], v[0:1]
	v_pk_mov_b32 v[68:69], v[0:1], v[0:1]
	v_pk_mov_b32 v[70:71], v[0:1], v[0:1]
	v_pk_mov_b32 v[72:73], v[0:1], v[0:1]
	v_pk_mov_b32 v[74:75], v[0:1], v[0:1]
	v_pk_mov_b32 v[76:77], v[0:1], v[0:1]
	v_pk_mov_b32 v[78:79], v[0:1], v[0:1]
	v_pk_mov_b32 v[80:81], v[0:1], v[0:1]
	v_pk_mov_b32 v[82:83], v[0:1], v[0:1]
	v_pk_mov_b32 v[84:85], v[0:1], v[0:1]
	v_pk_mov_b32 v[86:87], v[0:1], v[0:1]
	v_pk_mov_b32 v[88:89], v[0:1], v[0:1]
	v_pk_mov_b32 v[90:91], v[0:1], v[0:1]
	v_pk_mov_b32 v[92:93], v[0:1], v[0:1]
	v_pk_mov_b32 v[94:95], v[0:1], v[0:1]
	v_pk_mov_b32 v[96:97], v[0:1], v[0:1]
	v_pk_mov_b32 v[98:99], v[0:1], v[0:1]
	v_pk_mov_b32 v[100:101], v[0:1], v[0:1]
	v_pk_mov_b32 v[102:103], v[0:1], v[0:1]
	v_pk_mov_b32 v[104:105], v[0:1], v[0:1]
	v_pk_mov_b32 v[106:107], v[0:1], v[0:1]
	v_pk_mov_b32 v[108:109], v[0:1], v[0:1]
	v_pk_mov_b32 v[110:111], v[0:1], v[0:1]
	v_pk_mov_b32 v[112:113], v[0:1], v[0:1]
	v_pk_mov_b32 v[114:115], v[0:1], v[0:1]
	v_pk_mov_b32 v[116:117], v[0:1], v[0:1]
	v_pk_mov_b32 v[118:119], v[0:1], v[0:1]
	v_pk_mov_b32 v[120:121], v[0:1], v[0:1]
	v_pk_mov_b32 v[122:123], v[0:1], v[0:1]
	v_pk_mov_b32 v[124:125], v[0:1], v[0:1]
	v_pk_mov_b32 v[126:127], v[0:1], v[0:1]

; #define PG8_BAR __builtin_amdgcn_s_barrier()
; template <class Epi>
; __device__ __forceinline__ void gemm_phase(LAS unsigned char* lds, const int tid, const Gemm g, const StaticOrder& S, const Epi& E) {
;     ...
;     f32x4 acc[2][2][4][2];
; #pragma unroll
;     for (int a = 0; a < 2; ++a)
; #pragma unroll
;         for (int b = 0; b < 2; ++b)
; #pragma unroll
;             for (int m = 0; m < 4; ++m)
; #pragma unroll
;                 for (int n = 0; n < 2; ++n) acc[a][b][m][n] = (f32x4){0.f, 0.f, 0.f, 0.f};
;     ...
; #pragma unroll
;         for (int a = 0; a < 2; ++a)
; #pragma unroll
;             for (int b = 0; b < 2; ++b)
; #pragma unroll
;                 for (int m = 0; m < 4; ++m)
; #pragma unroll
;                     for (int n = 0; n < 2; ++n) acc[a][b][m][n] = (f32x4){0.f, 0.f, 0.f, 0.f};
;         cur = nxt; cA = nA; cB = nB; ++ui;
;         if (wr == 1) PG8_BAR;
.LBB0_904:
	v_mov_b32_e32 v155, 0
	s_andn2_b64 vcc, exec, s[18:19]
	v_mov_b32_e32 v154, 0
	v_mov_b32_e32 v157, 0
	v_mov_b32_e32 v156, 0
	v_mov_b32_e32 v159, 0
	v_mov_b32_e32 v158, 0
	v_mov_b32_e32 v161, 0
	v_mov_b32_e32 v160, 0
	v_mov_b32_e32 v153, 0
	v_mov_b32_e32 v152, 0
	v_mov_b32_e32 v151, 0
	v_mov_b32_e32 v150, 0
	v_mov_b32_e32 v149, 0
	v_mov_b32_e32 v148, 0
	v_mov_b32_e32 v147, 0
	v_mov_b32_e32 v146, 0
	v_mov_b32_e32 v121, 0
	v_mov_b32_e32 v120, 0
	v_mov_b32_e32 v119, 0
	v_mov_b32_e32 v118, 0
	v_mov_b32_e32 v117, 0
	v_mov_b32_e32 v116, 0
	v_mov_b32_e32 v115, 0
	v_mov_b32_e32 v114, 0
	v_mov_b32_e32 v105, 0
	v_mov_b32_e32 v104, 0
	v_mov_b32_e32 v103, 0
	v_mov_b32_e32 v102, 0
	v_mov_b32_e32 v101, 0
	v_mov_b32_e32 v100, 0
	v_mov_b32_e32 v99, 0
	v_mov_b32_e32 v98, 0
	v_mov_b32_e32 v169, 0
	v_mov_b32_e32 v168, 0
	v_mov_b32_e32 v167, 0
	v_mov_b32_e32 v166, 0
	v_mov_b32_e32 v165, 0
	v_mov_b32_e32 v164, 0
	v_mov_b32_e32 v163, 0
	v_mov_b32_e32 v162, 0
	v_mov_b32_e32 v145, 0
	v_mov_b32_e32 v144, 0
	v_mov_b32_e32 v127, 0
	v_mov_b32_e32 v126, 0
	v_mov_b32_e32 v125, 0
	v_mov_b32_e32 v124, 0
	v_mov_b32_e32 v123, 0
	v_mov_b32_e32 v122, 0
	v_mov_b32_e32 v113, 0
	v_mov_b32_e32 v112, 0
	v_mov_b32_e32 v111, 0
	v_mov_b32_e32 v110, 0
	v_mov_b32_e32 v109, 0
	v_mov_b32_e32 v108, 0
	v_mov_b32_e32 v107, 0
	v_mov_b32_e32 v106, 0
	v_mov_b32_e32 v97, 0
	v_mov_b32_e32 v96, 0
	v_mov_b32_e32 v95, 0
	v_mov_b32_e32 v94, 0
	v_mov_b32_e32 v93, 0
	v_mov_b32_e32 v92, 0
	v_mov_b32_e32 v91, 0
	v_mov_b32_e32 v90, 0
	v_mov_b32_e32 v73, 0
	v_mov_b32_e32 v72, 0
	v_mov_b32_e32 v75, 0
	v_mov_b32_e32 v74, 0
	v_mov_b32_e32 v77, 0
	v_mov_b32_e32 v76, 0
	v_mov_b32_e32 v79, 0
	v_mov_b32_e32 v78, 0
	v_mov_b32_e32 v71, 0
	v_mov_b32_e32 v70, 0
	v_mov_b32_e32 v69, 0
	v_mov_b32_e32 v68, 0
	v_mov_b32_e32 v67, 0
	v_mov_b32_e32 v66, 0
	v_mov_b32_e32 v65, 0
	v_mov_b32_e32 v64, 0
	v_mov_b32_e32 v55, 0
	v_mov_b32_e32 v54, 0
	v_mov_b32_e32 v53, 0
	v_mov_b32_e32 v52, 0
	v_mov_b32_e32 v51, 0
	v_mov_b32_e32 v50, 0
	v_mov_b32_e32 v49, 0
	v_mov_b32_e32 v48, 0
	v_mov_b32_e32 v39, 0
	v_mov_b32_e32 v38, 0
	v_mov_b32_e32 v37, 0
	v_mov_b32_e32 v36, 0
	v_mov_b32_e32 v35, 0
	v_mov_b32_e32 v34, 0
	v_mov_b32_e32 v33, 0
	v_mov_b32_e32 v32, 0
	v_mov_b32_e32 v87, 0
	v_mov_b32_e32 v86, 0
	v_mov_b32_e32 v85, 0
	v_mov_b32_e32 v84, 0
	v_mov_b32_e32 v83, 0
	v_mov_b32_e32 v82, 0
	v_mov_b32_e32 v81, 0
	v_mov_b32_e32 v80, 0
	v_mov_b32_e32 v63, 0
	v_mov_b32_e32 v62, 0
	v_mov_b32_e32 v61, 0
	v_mov_b32_e32 v60, 0
	v_mov_b32_e32 v59, 0
	v_mov_b32_e32 v58, 0
	v_mov_b32_e32 v57, 0
	v_mov_b32_e32 v56, 0
	v_mov_b32_e32 v47, 0
	v_mov_b32_e32 v46, 0
	v_mov_b32_e32 v45, 0
	v_mov_b32_e32 v44, 0
	v_mov_b32_e32 v43, 0
	v_mov_b32_e32 v42, 0
	v_mov_b32_e32 v41, 0
	v_mov_b32_e32 v40, 0
	v_mov_b32_e32 v31, 0
	v_mov_b32_e32 v30, 0
	v_mov_b32_e32 v29, 0
	v_mov_b32_e32 v28, 0
	v_mov_b32_e32 v27, 0
	v_mov_b32_e32 v26, 0
	v_mov_b32_e32 v25, 0
	v_mov_b32_e32 v24, 0
	s_cbranch_vccnz .LBB0_908
	s_add_u32 s56, s26, 0x100
	v_mov_b32_e32 v0, 0
	v_mov_b32_e32 v1, 0
	s_addc_u32 s57, s27, 0
	s_mov_b32 s28, 0
	v_pk_mov_b32 v[2:3], v[0:1], v[0:1]
	v_pk_mov_b32 v[4:5], v[0:1], v[0:1]
	v_pk_mov_b32 v[6:7], v[0:1], v[0:1]
	v_pk_mov_b32 v[8:9], v[0:1], v[0:1]
	v_pk_mov_b32 v[10:11], v[0:1], v[0:1]
	v_pk_mov_b32 v[12:13], v[0:1], v[0:1]
	v_pk_mov_b32 v[14:15], v[0:1], v[0:1]
	v_pk_mov_b32 v[16:17], v[0:1], v[0:1]
	v_pk_mov_b32 v[18:19], v[0:1], v[0:1]
	v_pk_mov_b32 v[20:21], v[0:1], v[0:1]
	v_pk_mov_b32 v[22:23], v[0:1], v[0:1]
	v_pk_mov_b32 v[24:25], v[0:1], v[0:1]
	v_pk_mov_b32 v[26:27], v[0:1], v[0:1]
	v_pk_mov_b32 v[28:29], v[0:1], v[0:1]
	v_pk_mov_b32 v[30:31], v[0:1], v[0:1]
	v_pk_mov_b32 v[32:33], v[0:1], v[0:1]
	v_pk_mov_b32 v[34:35], v[0:1], v[0:1]
	v_pk_mov_b32 v[36:37], v[0:1], v[0:1]
	v_pk_mov_b32 v[38:39], v[0:1], v[0:1]
	v_pk_mov_b32 v[40:41], v[0:1], v[0:1]
	v_pk_mov_b32 v[42:43], v[0:1], v[0:1]
	v_pk_mov_b32 v[44:45], v[0:1], v[0:1]
	v_pk_mov_b32 v[46:47], v[0:1], v[0:1]
	v_pk_mov_b32 v[48:49], v[0:1], v[0:1]
	v_pk_mov_b32 v[50:51], v[0:1], v[0:1]
	v_pk_mov_b32 v[52:53], v[0:1], v[0:1]
	v_pk_mov_b32 v[54:55], v[0:1], v[0:1]
	v_pk_mov_b32 v[56:57], v[0:1], v[0:1]
	v_pk_mov_b32 v[58:59], v[0:1], v[0:1]
	v_pk_mov_b32 v[60:61], v[0:1], v[0:1]
	v_pk_mov_b32 v[62:63], v[0:1], v[0:1]
	v_pk_mov_b32 v[64:65], v[0:1], v[0:1]
	v_pk_mov_b32 v[66:67], v[0:1], v[0:1]
	v_pk_mov_b32 v[68:69], v[0:1], v[0:1]
	v_pk_mov_b32 v[70:71], v[0:1], v[0:1]
	v_pk_mov_b32 v[72:73], v[0:1], v[0:1]
	v_pk_mov_b32 v[74:75], v[0:1], v[0:1]
	v_pk_mov_b32 v[76:77], v[0:1], v[0:1]
	v_pk_mov_b32 v[78:79], v[0:1], v[0:1]
	v_pk_mov_b32 v[80:81], v[0:1], v[0:1]
	v_pk_mov_b32 v[82:83], v[0:1], v[0:1]
	v_pk_mov_b32 v[84:85], v[0:1], v[0:1]
	v_pk_mov_b32 v[86:87], v[0:1], v[0:1]
	v_pk_mov_b32 v[88:89], v[0:1], v[0:1]
	v_pk_mov_b32 v[90:91], v[0:1], v[0:1]
	v_pk_mov_b32 v[92:93], v[0:1], v[0:1]
	v_pk_mov_b32 v[94:95], v[0:1], v[0:1]
	v_pk_mov_b32 v[96:97], v[0:1], v[0:1]
	v_pk_mov_b32 v[98:99], v[0:1], v[0:1]
	v_pk_mov_b32 v[100:101], v[0:1], v[0:1]
	v_pk_mov_b32 v[102:103], v[0:1], v[0:1]
	v_pk_mov_b32 v[104:105], v[0:1], v[0:1]
	v_pk_mov_b32 v[106:107], v[0:1], v[0:1]
	v_pk_mov_b32 v[108:109], v[0:1], v[0:1]
	v_pk_mov_b32 v[110:111], v[0:1], v[0:1]
	v_pk_mov_b32 v[112:113], v[0:1], v[0:1]
	v_pk_mov_b32 v[114:115], v[0:1], v[0:1]
	v_pk_mov_b32 v[116:117], v[0:1], v[0:1]
	v_pk_mov_b32 v[118:119], v[0:1], v[0:1]
	v_pk_mov_b32 v[120:121], v[0:1], v[0:1]
	v_pk_mov_b32 v[122:123], v[0:1], v[0:1]
	v_pk_mov_b32 v[124:125], v[0:1], v[0:1]
	v_pk_mov_b32 v[126:127], v[0:1], v[0:1]

; #define PG8_BAR __builtin_amdgcn_s_barrier()
; template <class Epi>
; __device__ __forceinline__ void gemm_phase(LAS unsigned char* lds, const int tid, const Gemm g, const StaticOrder& S, const Epi& E) {
;     ...
; #pragma unroll
;         for (int a = 0; a < 2; ++a)
; #pragma unroll
;             for (int b = 0; b < 2; ++b)
; #pragma unroll
;                 for (int m = 0; m < 4; ++m)
; #pragma unroll
;                     for (int n = 0; n < 2; ++n) acc[a][b][m][n] = (f32x4){0.f, 0.f, 0.f, 0.f};
;         cur = nxt; cA = nA; cB = nB; ++ui;
;         if (wr == 1) PG8_BAR;
.Lzskip_5:
	s_and_b64 s[30:31], s[2:3], exec
	s_cselect_b32 s19, s23, s29
	s_cselect_b32 s21, s22, s28
	s_cselect_b32 s52, s25, s27
	s_cselect_b32 s53, s24, s26
	s_add_u32 s54, s26, 0x100
	s_addc_u32 s55, s27, 0
	s_add_u32 s26, s28, 0x10080
	v_mov_b32_e32 v0, 0
	v_mov_b32_e32 v1, 0
	s_addc_u32 s27, s29, 0
	s_mov_b32 s28, 0
	v_pk_mov_b32 v[2:3], v[0:1], v[0:1]
	v_pk_mov_b32 v[4:5], v[0:1], v[0:1]
	v_pk_mov_b32 v[6:7], v[0:1], v[0:1]
	v_pk_mov_b32 v[8:9], v[0:1], v[0:1]
	v_pk_mov_b32 v[10:11], v[0:1], v[0:1]
	v_pk_mov_b32 v[12:13], v[0:1], v[0:1]
	v_pk_mov_b32 v[14:15], v[0:1], v[0:1]
	v_pk_mov_b32 v[16:17], v[0:1], v[0:1]
	v_pk_mov_b32 v[18:19], v[0:1], v[0:1]
	v_pk_mov_b32 v[20:21], v[0:1], v[0:1]
	v_pk_mov_b32 v[22:23], v[0:1], v[0:1]
	v_pk_mov_b32 v[24:25], v[0:1], v[0:1]
	v_pk_mov_b32 v[26:27], v[0:1], v[0:1]
	v_pk_mov_b32 v[28:29], v[0:1], v[0:1]
	v_pk_mov_b32 v[30:31], v[0:1], v[0:1]
	v_pk_mov_b32 v[32:33], v[0:1], v[0:1]
	v_pk_mov_b32 v[34:35], v[0:1], v[0:1]
	v_pk_mov_b32 v[36:37], v[0:1], v[0:1]
	v_pk_mov_b32 v[38:39], v[0:1], v[0:1]
	v_pk_mov_b32 v[40:41], v[0:1], v[0:1]
	v_pk_mov_b32 v[42:43], v[0:1], v[0:1]
	v_pk_mov_b32 v[44:45], v[0:1], v[0:1]
	v_pk_mov_b32 v[46:47], v[0:1], v[0:1]
	v_pk_mov_b32 v[48:49], v[0:1], v[0:1]
	v_pk_mov_b32 v[50:51], v[0:1], v[0:1]
	v_pk_mov_b32 v[52:53], v[0:1], v[0:1]
	v_pk_mov_b32 v[54:55], v[0:1], v[0:1]
	v_pk_mov_b32 v[56:57], v[0:1], v[0:1]
	v_pk_mov_b32 v[58:59], v[0:1], v[0:1]
	v_pk_mov_b32 v[60:61], v[0:1], v[0:1]
	v_pk_mov_b32 v[62:63], v[0:1], v[0:1]
	v_pk_mov_b32 v[64:65], v[0:1], v[0:1]
	v_pk_mov_b32 v[66:67], v[0:1], v[0:1]
	v_pk_mov_b32 v[68:69], v[0:1], v[0:1]
	v_pk_mov_b32 v[70:71], v[0:1], v[0:1]
	v_pk_mov_b32 v[72:73], v[0:1], v[0:1]
	v_pk_mov_b32 v[74:75], v[0:1], v[0:1]
	v_pk_mov_b32 v[76:77], v[0:1], v[0:1]
	v_pk_mov_b32 v[78:79], v[0:1], v[0:1]
	v_pk_mov_b32 v[80:81], v[0:1], v[0:1]
	v_pk_mov_b32 v[82:83], v[0:1], v[0:1]
	v_pk_mov_b32 v[84:85], v[0:1], v[0:1]
	v_pk_mov_b32 v[86:87], v[0:1], v[0:1]
	v_pk_mov_b32 v[88:89], v[0:1], v[0:1]
	v_pk_mov_b32 v[90:91], v[0:1], v[0:1]
	v_pk_mov_b32 v[92:93], v[0:1], v[0:1]
	v_pk_mov_b32 v[94:95], v[0:1], v[0:1]
	v_pk_mov_b32 v[96:97], v[0:1], v[0:1]
	v_pk_mov_b32 v[98:99], v[0:1], v[0:1]
	v_pk_mov_b32 v[100:101], v[0:1], v[0:1]
	v_pk_mov_b32 v[102:103], v[0:1], v[0:1]
	v_pk_mov_b32 v[104:105], v[0:1], v[0:1]
	v_pk_mov_b32 v[106:107], v[0:1], v[0:1]
	v_pk_mov_b32 v[108:109], v[0:1], v[0:1]
	v_pk_mov_b32 v[110:111], v[0:1], v[0:1]
	v_pk_mov_b32 v[112:113], v[0:1], v[0:1]
	v_pk_mov_b32 v[114:115], v[0:1], v[0:1]
	v_pk_mov_b32 v[116:117], v[0:1], v[0:1]
	v_pk_mov_b32 v[118:119], v[0:1], v[0:1]
	v_pk_mov_b32 v[120:121], v[0:1], v[0:1]
	v_pk_mov_b32 v[122:123], v[0:1], v[0:1]
	v_pk_mov_b32 v[124:125], v[0:1], v[0:1]
	v_pk_mov_b32 v[126:127], v[0:1], v[0:1]

; #define PG8_BAR __builtin_amdgcn_s_barrier()
; template <class Epi>
; __device__ __forceinline__ void gemm_phase(LAS unsigned char* lds, const int tid, const Gemm g, const StaticOrder& S, const Epi& E) {
;     ...
; #pragma unroll
;         for (int a = 0; a < 2; ++a)
; #pragma unroll
;             for (int b = 0; b < 2; ++b)
; #pragma unroll
;                 for (int m = 0; m < 4; ++m)
; #pragma unroll
;                     for (int n = 0; n < 2; ++n) acc[a][b][m][n] = (f32x4){0.f, 0.f, 0.f, 0.f};
;         cur = nxt; cA = nA; cB = nB; ++ui;
;         if (wr == 1) PG8_BAR;
.Lzskip_9:
	s_and_b64 s[40:41], s[2:3], exec
	s_cselect_b32 s27, s31, s39
	s_cselect_b32 s29, s30, s38
	s_cselect_b32 s33, s35, s37
	s_cselect_b32 s61, s34, s36
	s_add_u32 s62, s36, 0x100
	s_addc_u32 s63, s37, 0
	s_add_u32 s36, s38, 0x40080
	v_mov_b32_e32 v0, 0
	v_mov_b32_e32 v1, 0
	s_addc_u32 s37, s39, 0
	s_mov_b32 s38, 0
	v_pk_mov_b32 v[2:3], v[0:1], v[0:1]
	v_pk_mov_b32 v[4:5], v[0:1], v[0:1]
	v_pk_mov_b32 v[6:7], v[0:1], v[0:1]
	v_pk_mov_b32 v[8:9], v[0:1], v[0:1]
	v_pk_mov_b32 v[10:11], v[0:1], v[0:1]
	v_pk_mov_b32 v[12:13], v[0:1], v[0:1]
	v_pk_mov_b32 v[14:15], v[0:1], v[0:1]
	v_pk_mov_b32 v[16:17], v[0:1], v[0:1]
	v_pk_mov_b32 v[18:19], v[0:1], v[0:1]
	v_pk_mov_b32 v[20:21], v[0:1], v[0:1]
	v_pk_mov_b32 v[22:23], v[0:1], v[0:1]
	v_pk_mov_b32 v[24:25], v[0:1], v[0:1]
	v_pk_mov_b32 v[26:27], v[0:1], v[0:1]
	v_pk_mov_b32 v[28:29], v[0:1], v[0:1]
	v_pk_mov_b32 v[30:31], v[0:1], v[0:1]
	v_pk_mov_b32 v[32:33], v[0:1], v[0:1]
	v_pk_mov_b32 v[34:35], v[0:1], v[0:1]
	v_pk_mov_b32 v[36:37], v[0:1], v[0:1]
	v_pk_mov_b32 v[38:39], v[0:1], v[0:1]
	v_pk_mov_b32 v[44:45], v[0:1], v[0:1]
	v_pk_mov_b32 v[46:47], v[0:1], v[0:1]
	v_pk_mov_b32 v[56:57], v[0:1], v[0:1]
	v_pk_mov_b32 v[58:59], v[0:1], v[0:1]
	v_pk_mov_b32 v[72:73], v[0:1], v[0:1]
	v_pk_mov_b32 v[74:75], v[0:1], v[0:1]
	v_pk_mov_b32 v[76:77], v[0:1], v[0:1]
	v_pk_mov_b32 v[78:79], v[0:1], v[0:1]
	v_pk_mov_b32 v[84:85], v[0:1], v[0:1]
	v_pk_mov_b32 v[86:87], v[0:1], v[0:1]
	v_pk_mov_b32 v[88:89], v[0:1], v[0:1]
	v_pk_mov_b32 v[90:91], v[0:1], v[0:1]
	v_pk_mov_b32 v[92:93], v[0:1], v[0:1]
	v_pk_mov_b32 v[94:95], v[0:1], v[0:1]
	v_pk_mov_b32 v[96:97], v[0:1], v[0:1]
	v_pk_mov_b32 v[98:99], v[0:1], v[0:1]
	v_pk_mov_b32 v[104:105], v[0:1], v[0:1]
	v_pk_mov_b32 v[106:107], v[0:1], v[0:1]
	v_pk_mov_b32 v[108:109], v[0:1], v[0:1]
	v_pk_mov_b32 v[110:111], v[0:1], v[0:1]
	v_pk_mov_b32 v[112:113], v[0:1], v[0:1]
	v_pk_mov_b32 v[114:115], v[0:1], v[0:1]
	v_pk_mov_b32 v[116:117], v[0:1], v[0:1]
	v_pk_mov_b32 v[118:119], v[0:1], v[0:1]
	v_pk_mov_b32 v[124:125], v[0:1], v[0:1]
	v_pk_mov_b32 v[126:127], v[0:1], v[0:1]
	v_pk_mov_b32 v[128:129], v[0:1], v[0:1]
	v_pk_mov_b32 v[130:131], v[0:1], v[0:1]
	v_pk_mov_b32 v[132:133], v[0:1], v[0:1]
	v_pk_mov_b32 v[134:135], v[0:1], v[0:1]
	v_pk_mov_b32 v[136:137], v[0:1], v[0:1]
	v_pk_mov_b32 v[138:139], v[0:1], v[0:1]
	v_pk_mov_b32 v[144:145], v[0:1], v[0:1]
	v_pk_mov_b32 v[146:147], v[0:1], v[0:1]
	v_pk_mov_b32 v[148:149], v[0:1], v[0:1]
	v_pk_mov_b32 v[150:151], v[0:1], v[0:1]
	v_pk_mov_b32 v[152:153], v[0:1], v[0:1]
	v_pk_mov_b32 v[154:155], v[0:1], v[0:1]
	v_pk_mov_b32 v[156:157], v[0:1], v[0:1]
	v_pk_mov_b32 v[158:159], v[0:1], v[0:1]
	v_pk_mov_b32 v[164:165], v[0:1], v[0:1]
	v_pk_mov_b32 v[166:167], v[0:1], v[0:1]
	v_pk_mov_b32 v[168:169], v[0:1], v[0:1]
	v_pk_mov_b32 v[170:171], v[0:1], v[0:1]

; #define PG8_BAR __builtin_amdgcn_s_barrier()
; template <class Epi>
; __device__ __forceinline__ void gemm_phase(LAS unsigned char* lds, const int tid, const Gemm g, const StaticOrder& S, const Epi& E) {
;     ...
; #pragma unroll
;         for (int a = 0; a < 2; ++a)
; #pragma unroll
;             for (int b = 0; b < 2; ++b)
; #pragma unroll
;                 for (int m = 0; m < 4; ++m)
; #pragma unroll
;                     for (int n = 0; n < 2; ++n) acc[a][b][m][n] = (f32x4){0.f, 0.f, 0.f, 0.f};
;         cur = nxt; cA = nA; cB = nB; ++ui;
;         if (wr == 1) PG8_BAR;
.Lzskip_10:
	s_and_b64 s[40:41], s[4:5], exec
	s_cselect_b32 s25, s29, s39
	s_cselect_b32 s27, s28, s38
	s_cselect_b32 s35, s31, s37
	s_cselect_b32 s59, s30, s36
	s_add_u32 s60, s36, 0x100
	s_addc_u32 s61, s37, 0
	s_add_u32 s36, s38, 0x40080
	v_mov_b32_e32 v0, 0
	v_mov_b32_e32 v1, 0
	s_addc_u32 s37, s39, 0
	s_mov_b32 s38, 0
	v_pk_mov_b32 v[2:3], v[0:1], v[0:1]
	v_pk_mov_b32 v[4:5], v[0:1], v[0:1]
	v_pk_mov_b32 v[6:7], v[0:1], v[0:1]
	v_pk_mov_b32 v[8:9], v[0:1], v[0:1]
	v_pk_mov_b32 v[10:11], v[0:1], v[0:1]
	v_pk_mov_b32 v[12:13], v[0:1], v[0:1]
	v_pk_mov_b32 v[14:15], v[0:1], v[0:1]
	v_pk_mov_b32 v[16:17], v[0:1], v[0:1]
	v_pk_mov_b32 v[18:19], v[0:1], v[0:1]
	v_pk_mov_b32 v[20:21], v[0:1], v[0:1]
	v_pk_mov_b32 v[22:23], v[0:1], v[0:1]
	v_pk_mov_b32 v[24:25], v[0:1], v[0:1]
	v_pk_mov_b32 v[26:27], v[0:1], v[0:1]
	v_pk_mov_b32 v[28:29], v[0:1], v[0:1]
	v_pk_mov_b32 v[30:31], v[0:1], v[0:1]
	v_pk_mov_b32 v[32:33], v[0:1], v[0:1]
	v_pk_mov_b32 v[34:35], v[0:1], v[0:1]
	v_pk_mov_b32 v[36:37], v[0:1], v[0:1]
	v_pk_mov_b32 v[38:39], v[0:1], v[0:1]
	v_pk_mov_b32 v[40:41], v[0:1], v[0:1]
	v_pk_mov_b32 v[42:43], v[0:1], v[0:1]
	v_pk_mov_b32 v[44:45], v[0:1], v[0:1]
	v_pk_mov_b32 v[46:47], v[0:1], v[0:1]
	v_pk_mov_b32 v[48:49], v[0:1], v[0:1]
	v_pk_mov_b32 v[50:51], v[0:1], v[0:1]
	v_pk_mov_b32 v[52:53], v[0:1], v[0:1]
	v_pk_mov_b32 v[54:55], v[0:1], v[0:1]
	v_pk_mov_b32 v[56:57], v[0:1], v[0:1]
	v_pk_mov_b32 v[58:59], v[0:1], v[0:1]
	v_pk_mov_b32 v[60:61], v[0:1], v[0:1]
	v_pk_mov_b32 v[62:63], v[0:1], v[0:1]
	v_pk_mov_b32 v[64:65], v[0:1], v[0:1]
	v_pk_mov_b32 v[66:67], v[0:1], v[0:1]
	v_pk_mov_b32 v[68:69], v[0:1], v[0:1]
	v_pk_mov_b32 v[70:71], v[0:1], v[0:1]
	v_pk_mov_b32 v[72:73], v[0:1], v[0:1]
	v_pk_mov_b32 v[74:75], v[0:1], v[0:1]
	v_pk_mov_b32 v[76:77], v[0:1], v[0:1]
	v_pk_mov_b32 v[78:79], v[0:1], v[0:1]
	v_pk_mov_b32 v[80:81], v[0:1], v[0:1]
	v_pk_mov_b32 v[82:83], v[0:1], v[0:1]
	v_pk_mov_b32 v[84:85], v[0:1], v[0:1]
	v_pk_mov_b32 v[86:87], v[0:1], v[0:1]
	v_pk_mov_b32 v[88:89], v[0:1], v[0:1]
	v_pk_mov_b32 v[90:91], v[0:1], v[0:1]
	v_pk_mov_b32 v[92:93], v[0:1], v[0:1]
	v_pk_mov_b32 v[94:95], v[0:1], v[0:1]
	v_pk_mov_b32 v[96:97], v[0:1], v[0:1]
	v_pk_mov_b32 v[98:99], v[0:1], v[0:1]
	v_pk_mov_b32 v[100:101], v[0:1], v[0:1]
	v_pk_mov_b32 v[102:103], v[0:1], v[0:1]
	v_pk_mov_b32 v[104:105], v[0:1], v[0:1]
	v_pk_mov_b32 v[106:107], v[0:1], v[0:1]
	v_pk_mov_b32 v[108:109], v[0:1], v[0:1]
	v_pk_mov_b32 v[110:111], v[0:1], v[0:1]
	v_pk_mov_b32 v[112:113], v[0:1], v[0:1]
	v_pk_mov_b32 v[114:115], v[0:1], v[0:1]
	v_pk_mov_b32 v[116:117], v[0:1], v[0:1]
	v_pk_mov_b32 v[118:119], v[0:1], v[0:1]
	v_pk_mov_b32 v[120:121], v[0:1], v[0:1]
	v_pk_mov_b32 v[122:123], v[0:1], v[0:1]
	v_pk_mov_b32 v[124:125], v[0:1], v[0:1]
	v_pk_mov_b32 v[126:127], v[0:1], v[0:1]
